# W_in GEMM tile-to-XCD remap: each XCD step covers an 8x8 block of (row,col) tiles instead of 2 rows x 32 cols (logical-block permutation for phase 4, first-tile offsets recomputed)
# baseline (speedup 1.0000x reference)
.LBB0_637:
	s_mov_b32 s100, s63
	s_lshr_b32 s98, s63, 6
	s_and_b32 s99, s63, 63
	s_lshr_b32 s101, s98, 2
	s_lshl_b32 s101, s101, 2
	s_lshr_b32 s63, s99, 4
	s_add_i32 s101, s101, s63
	s_and_b32 s98, s98, 3
	s_lshl_b32 s98, s98, 3
	s_bfe_u32 s63, s99, 0x30001
	s_add_i32 s98, s98, s63
	s_and_b32 s99, s99, 1
	s_lshl_b32 s63, s101, 6
	s_lshl_b32 s101, s101, 1
	s_add_i32 s101, s101, s99
	s_sub_i32 s101, 0x7f, s101
	s_lshl_b32 s101, s101, 19
	v_writelane_b32 v250, s101, 14
	s_mov_b32 s101, 0
	v_writelane_b32 v250, s101, 15
	s_lshl_b32 s101, s98, 1
	s_or_b32 s63, s63, s101
	s_or_b32 s63, s63, s99
	s_lshl_b32 s98, s98, 18
	v_writelane_b32 v250, s98, 16
	s_mov_b32 s98, 0
	v_writelane_b32 v250, s98, 17
	s_cmp_lt_i32 s8, 1
	s_cbranch_scc1 .LBB0_671
	v_mov_b32_e32 v8, v222
	v_readlane_b32 s10, v252, 47
	v_lshrrev_b32_e32 v0, 1, v8
	v_and_b32_e32 v3, 0xfffff9f, v8
	v_and_b32_e32 v0, 16, v0
	v_readlane_b32 s11, v252, 48
	s_add_u32 s2, s10, 0x1900000
	v_mad_u64_u32 v[182:183], s[4:5], v3, s56, v[0:1]
	s_addc_u32 s3, s11, 0
	v_readlane_b32 s4, v250, 14
	v_ashrrev_i32_e32 v2, 3, v8
	v_and_b32_e32 v3, 0x5f, v8
	v_readlane_b32 s5, v250, 15
	s_add_u32 s4, s2, s4
	v_mad_u32_u24 v183, v3, s56, v0
	s_addc_u32 s5, s3, s5
	v_readlane_b32 s6, v250, 16
	v_ashrrev_i32_e32 v3, 31, v2
	v_readlane_b32 s7, v250, 17
	s_add_u32 s6, s10, s6
	v_lshlrev_b64 v[4:5], 11, v[2:3]
	v_lshlrev_b32_e32 v0, 4, v8
	s_addc_u32 s7, s11, s7
	v_lshl_add_u64 v[6:7], s[4:5], 0, v[4:5]
	v_and_b32_e32 v0, 0x70, v0
	v_lshl_add_u64 v[184:185], v[6:7], 0, v[0:1]
	v_lshl_add_u64 v[6:7], s[6:7], 0, v[4:5]
	s_mov_b32 s5, 0x10000
	v_lshl_add_u64 v[186:187], v[6:7], 0, v[0:1]
	v_add_co_u32_e32 v6, vcc, s5, v184
	s_mov_b32 s1, 0x20000
	s_nop 0
	v_addc_co_u32_e32 v7, vcc, 0, v185, vcc
	v_add_co_u32_e32 v8, vcc, s1, v184
	s_mov_b32 s4, 0x30000
	s_nop 0
	v_addc_co_u32_e32 v9, vcc, 0, v185, vcc
	global_load_dwordx4 v[130:133], v[6:7], off
	global_load_dwordx4 v[134:137], v[8:9], off
	v_add_co_u32_e32 v6, vcc, s4, v184
	s_mov_b32 s4, 0x40000
	s_nop 0
	v_addc_co_u32_e32 v7, vcc, 0, v185, vcc
	v_add_co_u32_e32 v8, vcc, s4, v184
	s_mov_b32 s4, 0x50000
	s_nop 0
	v_addc_co_u32_e32 v9, vcc, 0, v185, vcc
	global_load_dwordx4 v[138:141], v[6:7], off
	global_load_dwordx4 v[146:149], v[8:9], off
	v_add_co_u32_e32 v6, vcc, s4, v184
	s_mov_b32 s4, 0x60000
	s_nop 0
	v_addc_co_u32_e32 v7, vcc, 0, v185, vcc
	v_add_co_u32_e32 v8, vcc, s4, v184
	s_mov_b32 s4, 0x70000
	s_nop 0
	v_addc_co_u32_e32 v9, vcc, 0, v185, vcc
	global_load_dwordx4 v[150:153], v[6:7], off
	global_load_dwordx4 v[154:157], v[8:9], off
	v_add_co_u32_e32 v6, vcc, s4, v184
	global_load_dwordx4 v[142:145], v[184:185], off
	global_load_dwordx4 v[162:165], v[186:187], off
	v_addc_co_u32_e32 v7, vcc, 0, v185, vcc
	v_add_co_u32_e32 v8, vcc, s5, v186
	v_mad_u64_u32 v[188:189], s[4:5], v2, s56, v[0:1]
	s_nop 0
	v_addc_co_u32_e32 v9, vcc, 0, v187, vcc
	global_load_dwordx4 v[158:161], v[6:7], off
	global_load_dwordx4 v[166:169], v[8:9], off
	v_add_co_u32_e32 v6, vcc, s1, v186
	v_lshl_add_u64 v[2:3], s[2:3], 0, v[4:5]
	s_nop 0
	v_addc_co_u32_e32 v7, vcc, 0, v187, vcc
	v_add_co_u32_e32 v8, vcc, 0x30000, v186
	v_lshl_add_u64 v[190:191], v[2:3], 0, v[0:1]
	s_nop 0
	v_addc_co_u32_e32 v9, vcc, 0, v187, vcc
	global_load_dwordx4 v[170:173], v[6:7], off
	global_load_dwordx4 v[174:177], v[8:9], off
	v_lshl_add_u64 v[2:3], s[10:11], 0, v[4:5]
	v_lshl_add_u64 v[192:193], v[2:3], 0, v[0:1]
	v_mov_b32_e32 v2, 0
	s_mov_b32 s0, 1
	s_mov_b32 s9, 0
	s_mov_b32 s2, 0
	s_mov_b32 s10, 0
	v_mov_b32_e32 v3, v2
	v_mov_b32_e32 v4, v2
	v_mov_b32_e32 v5, v2
	v_mov_b32_e32 v6, v2
	v_mov_b32_e32 v7, v2
	v_mov_b32_e32 v8, v2
	v_mov_b32_e32 v9, v2
	v_mov_b32_e32 v10, v2
	v_mov_b32_e32 v11, v2
	v_mov_b32_e32 v12, v2
	v_mov_b32_e32 v13, v2
	v_mov_b32_e32 v14, v2
	v_mov_b32_e32 v15, v2
	v_mov_b32_e32 v16, v2
	v_mov_b32_e32 v17, v2
	v_mov_b32_e32 v66, v2
	v_mov_b32_e32 v67, v2
	v_mov_b32_e32 v68, v2
	v_mov_b32_e32 v69, v2
	v_mov_b32_e32 v70, v2
	v_mov_b32_e32 v71, v2
	v_mov_b32_e32 v72, v2
	v_mov_b32_e32 v73, v2
	v_mov_b32_e32 v74, v2
	v_mov_b32_e32 v75, v2
	v_mov_b32_e32 v76, v2
	v_mov_b32_e32 v77, v2
	v_mov_b32_e32 v78, v2
	v_mov_b32_e32 v79, v2
	v_mov_b32_e32 v80, v2
	v_mov_b32_e32 v81, v2
	v_mov_b32_e32 v18, v2
	v_mov_b32_e32 v19, v2
	v_mov_b32_e32 v20, v2
	v_mov_b32_e32 v21, v2
	v_mov_b32_e32 v22, v2
	v_mov_b32_e32 v23, v2
	v_mov_b32_e32 v24, v2
	v_mov_b32_e32 v25, v2
	v_mov_b32_e32 v26, v2
	v_mov_b32_e32 v27, v2
	v_mov_b32_e32 v28, v2
	v_mov_b32_e32 v29, v2
	v_mov_b32_e32 v30, v2
	v_mov_b32_e32 v31, v2
	v_mov_b32_e32 v32, v2
	v_mov_b32_e32 v33, v2
	s_waitcnt vmcnt(23)
	v_mov_b32_e32 v82, v2
	v_mov_b32_e32 v83, v2
	v_mov_b32_e32 v84, v2
	v_mov_b32_e32 v85, v2
	s_waitcnt vmcnt(22)
	v_mov_b32_e32 v86, v2
	v_mov_b32_e32 v87, v2
	v_mov_b32_e32 v88, v2
	v_mov_b32_e32 v89, v2
	s_waitcnt vmcnt(21)
	v_mov_b32_e32 v90, v2
	v_mov_b32_e32 v91, v2
	v_mov_b32_e32 v92, v2
	v_mov_b32_e32 v93, v2
	s_waitcnt vmcnt(20)
	v_mov_b32_e32 v94, v2
	v_mov_b32_e32 v95, v2
	v_mov_b32_e32 v96, v2
	v_mov_b32_e32 v97, v2
	v_mov_b32_e32 v34, v2
	v_mov_b32_e32 v35, v2
	v_mov_b32_e32 v36, v2
	v_mov_b32_e32 v37, v2
	v_mov_b32_e32 v38, v2
	v_mov_b32_e32 v39, v2
	v_mov_b32_e32 v40, v2
	v_mov_b32_e32 v41, v2
	v_mov_b32_e32 v42, v2
	v_mov_b32_e32 v43, v2
	v_mov_b32_e32 v44, v2
	v_mov_b32_e32 v45, v2
	v_mov_b32_e32 v46, v2
	v_mov_b32_e32 v47, v2
	v_mov_b32_e32 v48, v2
	v_mov_b32_e32 v49, v2
	v_mov_b32_e32 v98, v2
	v_mov_b32_e32 v99, v2
	v_mov_b32_e32 v100, v2
	v_mov_b32_e32 v101, v2
	v_mov_b32_e32 v102, v2
	v_mov_b32_e32 v103, v2
	v_mov_b32_e32 v104, v2
	v_mov_b32_e32 v105, v2
	v_mov_b32_e32 v106, v2
	v_mov_b32_e32 v107, v2
	v_mov_b32_e32 v108, v2
	v_mov_b32_e32 v109, v2
	v_mov_b32_e32 v110, v2
	v_mov_b32_e32 v111, v2
	v_mov_b32_e32 v112, v2
	v_mov_b32_e32 v113, v2
	v_mov_b32_e32 v50, v2
	v_mov_b32_e32 v51, v2
	v_mov_b32_e32 v52, v2
	v_mov_b32_e32 v53, v2
	v_mov_b32_e32 v54, v2
	v_mov_b32_e32 v55, v2
	v_mov_b32_e32 v56, v2
	v_mov_b32_e32 v57, v2
	v_mov_b32_e32 v58, v2
	v_mov_b32_e32 v59, v2
	v_mov_b32_e32 v60, v2
	v_mov_b32_e32 v61, v2
	v_mov_b32_e32 v62, v2
	v_mov_b32_e32 v63, v2
	v_mov_b32_e32 v64, v2
	v_mov_b32_e32 v65, v2
	v_mov_b32_e32 v114, v2
	v_mov_b32_e32 v115, v2
	v_mov_b32_e32 v116, v2
	v_mov_b32_e32 v117, v2
	v_mov_b32_e32 v118, v2
	v_mov_b32_e32 v119, v2
	v_mov_b32_e32 v120, v2
	v_mov_b32_e32 v121, v2
	v_mov_b32_e32 v122, v2
	v_mov_b32_e32 v123, v2
	v_mov_b32_e32 v124, v2
	v_mov_b32_e32 v125, v2
	v_mov_b32_e32 v126, v2
	v_mov_b32_e32 v127, v2
	v_mov_b32_e32 v128, v2
	v_mov_b32_e32 v129, v2
	s_branch .LBB0_642

.LBB0_671:
	s_mov_b32 s63, s100
	s_mov_b64 s[0:1], 0

	.amdhsa_kernel _Z10hybrid_fwd6Paramsii
		.amdhsa_group_segment_fixed_size 79872
		.amdhsa_private_segment_fixed_size 0
		.amdhsa_kernarg_size 448
		.amdhsa_user_sgpr_count 2
		.amdhsa_user_sgpr_dispatch_ptr 0
		.amdhsa_user_sgpr_queue_ptr 0
		.amdhsa_user_sgpr_kernarg_segment_ptr 1
		.amdhsa_user_sgpr_dispatch_id 0
		.amdhsa_user_sgpr_kernarg_preload_length 0
		.amdhsa_user_sgpr_kernarg_preload_offset 0
		.amdhsa_user_sgpr_private_segment_size 0
		.amdhsa_uses_dynamic_stack 0
		.amdhsa_enable_private_segment 0
		.amdhsa_system_sgpr_workgroup_id_x 1
		.amdhsa_system_sgpr_workgroup_id_y 0
		.amdhsa_system_sgpr_workgroup_id_z 0
		.amdhsa_system_sgpr_workgroup_info 0
		.amdhsa_system_vgpr_workitem_id 2
		.amdhsa_next_free_vgpr 256
		.amdhsa_next_free_sgpr 102
		.amdhsa_accum_offset 256
		.amdhsa_reserve_vcc 1
		.amdhsa_float_round_mode_32 0
		.amdhsa_float_round_mode_16_64 0
		.amdhsa_float_denorm_mode_32 3
		.amdhsa_float_denorm_mode_16_64 3
		.amdhsa_dx10_clamp 1
		.amdhsa_ieee_mode 1
		.amdhsa_fp16_overflow 0
		.amdhsa_tg_split 0
		.amdhsa_exception_fp_ieee_invalid_op 0
		.amdhsa_exception_fp_denorm_src 0
		.amdhsa_exception_fp_ieee_div_zero 0
		.amdhsa_exception_fp_ieee_overflow 0
		.amdhsa_exception_fp_ieee_underflow 0
		.amdhsa_exception_fp_ieee_inexact 0
		.amdhsa_exception_int_div_zero 0
	.end_amdhsa_kernel

amdhsa.kernels:
  - .agpr_count:     0
    .args:
      - .offset:         0
        .size:           184
        .value_kind:     by_value
      - .offset:         184
        .size:           4
        .value_kind:     by_value
      - .offset:         188
        .size:           4
        .value_kind:     by_value
      - .offset:         192
        .size:           4
        .value_kind:     hidden_block_count_x
      - .offset:         196
        .size:           4
        .value_kind:     hidden_block_count_y
      - .offset:         200
        .size:           4
        .value_kind:     hidden_block_count_z
      - .offset:         204
        .size:           2
        .value_kind:     hidden_group_size_x
      - .offset:         206
        .size:           2
        .value_kind:     hidden_group_size_y
      - .offset:         208
        .size:           2
        .value_kind:     hidden_group_size_z
      - .offset:         210
        .size:           2
        .value_kind:     hidden_remainder_x
      - .offset:         212
        .size:           2
        .value_kind:     hidden_remainder_y
      - .offset:         214
        .size:           2
        .value_kind:     hidden_remainder_z
      - .offset:         232
        .size:           8
        .value_kind:     hidden_global_offset_x
      - .offset:         240
        .size:           8
        .value_kind:     hidden_global_offset_y
      - .offset:         248
        .size:           8
        .value_kind:     hidden_global_offset_z
      - .offset:         256
        .size:           2
        .value_kind:     hidden_grid_dims
      - .offset:         280
        .size:           8
        .value_kind:     hidden_multigrid_sync_arg
    .group_segment_fixed_size: 79872
    .kernarg_segment_align: 8
    .kernarg_segment_size: 448
    .language:       OpenCL C
    .language_version:
      - 2
      - 0
    .max_flat_workgroup_size: 256
    .name:           _Z10hybrid_fwd6Paramsii
    .private_segment_fixed_size: 0
    .sgpr_count:     108
    .sgpr_spill_count: 407
    .symbol:         _Z10hybrid_fwd6Paramsii.kd
    .uniform_work_group_size: 1
    .uses_dynamic_stack: false
    .vgpr_count:     256
    .vgpr_spill_count: 0
    .wavefront_size: 64
